# MLA hand loop LDS fragment prefetch distance 4 (was 5); otherwise v136
# speedup vs baseline: 1.0105x; 1.0105x over previous
.Lmf_loop:
	ds_read_b128 v[162:165], v216 offset:13312
	ds_read_b128 v[166:169], v216 offset:19968
	ds_read_b128 v[172:175], v216 offset:13344
	ds_read_b128 v[176:179], v216 offset:20000
	global_load_dwordx4 v[130:133], v235, s[14:15]
	global_load_dwordx4 v[134:137], v236, s[14:15]
	s_add_u32 s14, s14, 0x18000
	s_addc_u32 s15, s15, 0
	global_load_dwordx4 v[142:145], v237, s[12:13]
	s_add_u32 s12, s12, 0x80
	s_addc_u32 s13, s13, 0
	s_waitcnt lgkmcnt(3)
	v_mfma_f32_32x32x16_bf16 v[34:49], v[162:165], v[98:101], v[146:161]
	ds_read_b128 v[180:183], v216 offset:13376
	v_exp_f32_e32 v66, v66
	v_exp_f32_e32 v67, v67
	v_exp_f32_e32 v68, v68
	v_exp_f32_e32 v69, v69
	s_waitcnt lgkmcnt(3)
	v_mfma_f32_32x32x16_bf16 v[50:65], v[166:169], v[98:101], v[146:161]
	ds_read_b128 v[184:187], v216 offset:20032
	v_add_f32_e32 v171, v66, v171
	v_exp_f32_e32 v70, v70
	v_exp_f32_e32 v71, v71
	v_add_f32_e32 v171, v68, v171
	s_waitcnt lgkmcnt(3)
	v_mfma_f32_32x32x16_bf16 v[34:49], v[172:175], v[102:105], v[34:49]
	ds_read_b128 v[188:191], v216 offset:13408
	v_exp_f32_e32 v72, v72
	v_add_f32_e32 v197, v67, v69
	v_exp_f32_e32 v73, v73
	v_add_f32_e32 v171, v70, v171
	s_waitcnt lgkmcnt(3)
	v_mfma_f32_32x32x16_bf16 v[50:65], v[176:179], v[102:105], v[50:65]
	ds_read_b128 v[192:195], v216 offset:20064
	v_add_f32_e32 v197, v71, v197
	v_cvt_pk_bf16_f32 v66, v66, v67
	v_add_f32_e32 v171, v72, v171
	v_cvt_pk_bf16_f32 v67, v68, v69
	v_add_f32_e32 v197, v73, v197
	v_cvt_pk_bf16_f32 v68, v70, v71
	v_cvt_pk_bf16_f32 v69, v72, v73
	s_waitcnt lgkmcnt(3)
	v_mfma_f32_32x32x16_bf16 v[34:49], v[180:183], v[106:109], v[34:49]
	ds_read_b128 v[162:165], v216 offset:13440
	v_exp_f32_e32 v74, v74
	v_exp_f32_e32 v75, v75
	v_exp_f32_e32 v76, v76
	s_waitcnt lgkmcnt(3)
	v_mfma_f32_32x32x16_bf16 v[50:65], v[184:187], v[106:109], v[50:65]
	ds_read_b128 v[166:169], v216 offset:20096
	v_exp_f32_e32 v77, v77
	v_add_f32_e32 v171, v74, v171
	v_exp_f32_e32 v78, v78
	v_add_f32_e32 v197, v75, v197
	v_exp_f32_e32 v79, v79
	s_waitcnt lgkmcnt(3)
	v_mfma_f32_32x32x16_bf16 v[34:49], v[188:191], v[110:113], v[34:49]
	ds_read_b128 v[172:175], v216 offset:13472
	v_add_f32_e32 v171, v76, v171
	v_exp_f32_e32 v80, v80
	v_add_f32_e32 v197, v77, v197
	v_exp_f32_e32 v81, v81
	s_waitcnt lgkmcnt(3)
	v_mfma_f32_32x32x16_bf16 v[50:65], v[192:195], v[110:113], v[50:65]
	ds_read_b128 v[176:179], v216 offset:20128
	v_add_f32_e32 v171, v78, v171
	v_add_f32_e32 v197, v79, v197
	v_cvt_pk_bf16_f32 v74, v74, v75
	v_add_f32_e32 v171, v80, v171
	v_cvt_pk_bf16_f32 v75, v76, v77
	v_add_f32_e32 v197, v81, v197
	s_waitcnt lgkmcnt(3)
	v_mfma_f32_32x32x16_bf16 v[34:49], v[162:165], v[114:117], v[34:49]
	ds_read_b128 v[180:183], v217 offset:26624
	v_cvt_pk_bf16_f32 v76, v78, v79
	v_cvt_pk_bf16_f32 v77, v80, v81
	v_exp_f32_e32 v82, v82
	v_exp_f32_e32 v83, v83
	v_exp_f32_e32 v84, v84
	s_waitcnt lgkmcnt(3)
	v_mfma_f32_32x32x16_bf16 v[50:65], v[166:169], v[114:117], v[50:65]
	ds_read_b128 v[184:187], v217 offset:31232
	v_exp_f32_e32 v85, v85
	v_add_f32_e32 v171, v82, v171
	v_exp_f32_e32 v86, v86
	s_waitcnt lgkmcnt(3)
	v_mfma_f32_32x32x16_bf16 v[34:49], v[172:175], v[118:121], v[34:49]
	ds_read_b128 v[188:191], v217 offset:26656
	v_add_f32_e32 v197, v83, v197
	v_exp_f32_e32 v87, v87
	v_add_f32_e32 v171, v84, v171
	v_exp_f32_e32 v88, v88
	v_add_f32_e32 v197, v85, v197
	s_waitcnt lgkmcnt(3)
	v_mfma_f32_32x32x16_bf16 v[50:65], v[176:179], v[118:121], v[50:65]
	ds_read_b128 v[192:195], v217 offset:31264
	v_exp_f32_e32 v89, v89
	v_add_f32_e32 v171, v86, v171
	v_add_f32_e32 v197, v87, v197
	v_cvt_pk_bf16_f32 v82, v82, v83
	v_add_f32_e32 v171, v88, v171
	s_waitcnt lgkmcnt(3)
	v_mfma_f32_32x32x16_bf16 v[18:33], v[180:183], v[66:69], v[18:33]
	ds_read_b128 v[162:165], v217 offset:26688
	v_cvt_pk_bf16_f32 v83, v84, v85
	v_add_f32_e32 v197, v89, v197
	v_cvt_pk_bf16_f32 v84, v86, v87
	v_cvt_pk_bf16_f32 v85, v88, v89
	v_exp_f32_e32 v90, v90
	v_exp_f32_e32 v91, v91
	s_waitcnt lgkmcnt(3)
	v_mfma_f32_32x32x16_bf16 v[2:17], v[184:187], v[66:69], v[2:17]
	ds_read_b128 v[166:169], v217 offset:31296
	v_exp_f32_e32 v92, v92
	v_exp_f32_e32 v93, v93
	v_add_f32_e32 v171, v90, v171
	v_exp_f32_e32 v94, v94
	s_waitcnt lgkmcnt(3)
	v_mfma_f32_32x32x16_bf16 v[18:33], v[188:191], v[74:77], v[18:33]
	ds_read_b128 v[172:175], v217 offset:26720
	v_add_f32_e32 v197, v91, v197
	v_exp_f32_e32 v95, v95
	v_add_f32_e32 v171, v92, v171
	v_exp_f32_e32 v96, v96
	s_waitcnt lgkmcnt(3)
	v_mfma_f32_32x32x16_bf16 v[2:17], v[192:195], v[74:77], v[2:17]
	ds_read_b128 v[176:179], v217 offset:31328
	s_waitcnt vmcnt(3)
	v_add_u32_e32 v196, 0x8800, v215
	ds_write_b128 v228, v[122:125]
	ds_write_b128 v238, v[126:129]
	ds_write2_b64 v196, v[138:139], v[140:141] offset0:128 offset1:130
	v_add_f32_e32 v197, v93, v197
	v_exp_f32_e32 v97, v97
	v_add_f32_e32 v171, v94, v171
	v_add_f32_e32 v197, v95, v197
	v_cvt_pk_bf16_f32 v90, v90, v91
	s_waitcnt lgkmcnt(6)
	v_mfma_f32_32x32x16_bf16 v[18:33], v[162:165], v[82:85], v[18:33]
	v_add_f32_e32 v171, v96, v171
	v_cvt_pk_bf16_f32 v91, v92, v93
	v_add_f32_e32 v197, v97, v197
	v_cvt_pk_bf16_f32 v92, v94, v95
	v_cvt_pk_bf16_f32 v93, v96, v97
	v_max3_f32 v1, v34, v35, v36
	s_waitcnt lgkmcnt(5)
	v_mfma_f32_32x32x16_bf16 v[2:17], v[166:169], v[82:85], v[2:17]
	v_max3_f32 v170, v37, v38, v39
	v_max3_f32 v1, v1, v40, v41
	v_max3_f32 v170, v170, v42, v43
	v_max3_f32 v1, v1, v44, v45
	v_max3_f32 v170, v170, v46, v47
	v_max3_f32 v1, v1, v48, v49
	v_max3_f32 v170, v170, v50, v51
	s_waitcnt lgkmcnt(4)
	v_mfma_f32_32x32x16_bf16 v[18:33], v[172:175], v[90:93], v[18:33]
	v_max3_f32 v1, v1, v52, v53
	v_max3_f32 v170, v170, v54, v55
	v_max3_f32 v1, v1, v56, v57
	v_max3_f32 v170, v170, v58, v59
	v_max3_f32 v1, v1, v60, v61
	v_max3_f32 v170, v170, v62, v63
	s_waitcnt lgkmcnt(3)
	v_mfma_f32_32x32x16_bf16 v[2:17], v[176:179], v[90:93], v[2:17]
	v_max3_f32 v1, v1, v64, v65
	v_max_f32_e32 v1, v1, v170
	v_mov_b32_e32 v170, v1
	v_add_f32_e32 v171, v197, v171
	s_nop 0
	v_permlane32_swap_b32_e32 v1, v170
	v_max_f32_e32 v1, v1, v170
	v_cmp_lt_f32_e32 vcc, s93, v1
	s_cbranch_vccnz .Lmf_slow_0
.Lmf_join_0:
	s_waitcnt lgkmcnt(0)
	s_barrier
	ds_read_b128 v[162:165], v216 offset:0
	ds_read_b128 v[166:169], v216 offset:6656
	ds_read_b128 v[172:175], v216 offset:32
	ds_read_b128 v[176:179], v216 offset:6688
	global_load_dwordx4 v[122:125], v235, s[14:15]
	global_load_dwordx4 v[126:129], v236, s[14:15]
	s_add_u32 s14, s14, 0x18000
	s_addc_u32 s15, s15, 0
	global_load_dwordx4 v[138:141], v237, s[12:13]
	s_add_u32 s12, s12, 0x80
	s_addc_u32 s13, s13, 0
	s_waitcnt lgkmcnt(3)
	v_mfma_f32_32x32x16_bf16 v[66:81], v[162:165], v[98:101], v[146:161]
	ds_read_b128 v[180:183], v216 offset:64
	v_exp_f32_e32 v34, v34
	v_exp_f32_e32 v35, v35
	v_exp_f32_e32 v36, v36
	v_exp_f32_e32 v37, v37
	s_waitcnt lgkmcnt(3)
	v_mfma_f32_32x32x16_bf16 v[82:97], v[166:169], v[98:101], v[146:161]
	ds_read_b128 v[184:187], v216 offset:6720
	v_add_f32_e32 v171, v34, v171
	v_exp_f32_e32 v38, v38
	v_exp_f32_e32 v39, v39
	v_add_f32_e32 v171, v36, v171
	s_waitcnt lgkmcnt(3)
	v_mfma_f32_32x32x16_bf16 v[66:81], v[172:175], v[102:105], v[66:81]
	ds_read_b128 v[188:191], v216 offset:96
	v_exp_f32_e32 v40, v40
	v_add_f32_e32 v197, v35, v37
	v_exp_f32_e32 v41, v41
	v_add_f32_e32 v171, v38, v171
	s_waitcnt lgkmcnt(3)
	v_mfma_f32_32x32x16_bf16 v[82:97], v[176:179], v[102:105], v[82:97]
	ds_read_b128 v[192:195], v216 offset:6752
	v_add_f32_e32 v197, v39, v197
	v_cvt_pk_bf16_f32 v34, v34, v35
	v_add_f32_e32 v171, v40, v171
	v_cvt_pk_bf16_f32 v35, v36, v37
	v_add_f32_e32 v197, v41, v197
	v_cvt_pk_bf16_f32 v36, v38, v39
	v_cvt_pk_bf16_f32 v37, v40, v41
	s_waitcnt lgkmcnt(3)
	v_mfma_f32_32x32x16_bf16 v[66:81], v[180:183], v[106:109], v[66:81]
	ds_read_b128 v[162:165], v216 offset:128
	v_exp_f32_e32 v42, v42
	v_exp_f32_e32 v43, v43
	v_exp_f32_e32 v44, v44
	s_waitcnt lgkmcnt(3)
	v_mfma_f32_32x32x16_bf16 v[82:97], v[184:187], v[106:109], v[82:97]
	ds_read_b128 v[166:169], v216 offset:6784
	v_exp_f32_e32 v45, v45
	v_add_f32_e32 v171, v42, v171
	v_exp_f32_e32 v46, v46
	v_add_f32_e32 v197, v43, v197
	v_exp_f32_e32 v47, v47
	s_waitcnt lgkmcnt(3)
	v_mfma_f32_32x32x16_bf16 v[66:81], v[188:191], v[110:113], v[66:81]
	ds_read_b128 v[172:175], v216 offset:160
	v_add_f32_e32 v171, v44, v171
	v_exp_f32_e32 v48, v48
	v_add_f32_e32 v197, v45, v197
	v_exp_f32_e32 v49, v49
	s_waitcnt lgkmcnt(3)
	v_mfma_f32_32x32x16_bf16 v[82:97], v[192:195], v[110:113], v[82:97]
	ds_read_b128 v[176:179], v216 offset:6816
	v_add_f32_e32 v171, v46, v171
	v_add_f32_e32 v197, v47, v197
	v_cvt_pk_bf16_f32 v42, v42, v43
	v_add_f32_e32 v171, v48, v171
	v_cvt_pk_bf16_f32 v43, v44, v45
	v_add_f32_e32 v197, v49, v197
	s_waitcnt lgkmcnt(3)
	v_mfma_f32_32x32x16_bf16 v[66:81], v[162:165], v[114:117], v[66:81]
	ds_read_b128 v[180:183], v217 offset:35840
	v_cvt_pk_bf16_f32 v44, v46, v47
	v_cvt_pk_bf16_f32 v45, v48, v49
	v_exp_f32_e32 v50, v50
	v_exp_f32_e32 v51, v51
	v_exp_f32_e32 v52, v52
	s_waitcnt lgkmcnt(3)
	v_mfma_f32_32x32x16_bf16 v[82:97], v[166:169], v[114:117], v[82:97]
	ds_read_b128 v[184:187], v217 offset:40448
	v_exp_f32_e32 v53, v53
	v_add_f32_e32 v171, v50, v171
	v_exp_f32_e32 v54, v54
	s_waitcnt lgkmcnt(3)
	v_mfma_f32_32x32x16_bf16 v[66:81], v[172:175], v[118:121], v[66:81]
	ds_read_b128 v[188:191], v217 offset:35872
	v_add_f32_e32 v197, v51, v197
	v_exp_f32_e32 v55, v55
	v_add_f32_e32 v171, v52, v171
	v_exp_f32_e32 v56, v56
	v_add_f32_e32 v197, v53, v197
	s_waitcnt lgkmcnt(3)
	v_mfma_f32_32x32x16_bf16 v[82:97], v[176:179], v[118:121], v[82:97]
	ds_read_b128 v[192:195], v217 offset:40480
	v_exp_f32_e32 v57, v57
	v_add_f32_e32 v171, v54, v171
	v_add_f32_e32 v197, v55, v197
	v_cvt_pk_bf16_f32 v50, v50, v51
	v_add_f32_e32 v171, v56, v171
	s_waitcnt lgkmcnt(3)
	v_mfma_f32_32x32x16_bf16 v[18:33], v[180:183], v[34:37], v[18:33]
	ds_read_b128 v[162:165], v217 offset:35904
	v_cvt_pk_bf16_f32 v51, v52, v53
	v_add_f32_e32 v197, v57, v197
	v_cvt_pk_bf16_f32 v52, v54, v55
	v_cvt_pk_bf16_f32 v53, v56, v57
	v_exp_f32_e32 v58, v58
	v_exp_f32_e32 v59, v59
	s_waitcnt lgkmcnt(3)
	v_mfma_f32_32x32x16_bf16 v[2:17], v[184:187], v[34:37], v[2:17]
	ds_read_b128 v[166:169], v217 offset:40512
	v_exp_f32_e32 v60, v60
	v_exp_f32_e32 v61, v61
	v_add_f32_e32 v171, v58, v171
	v_exp_f32_e32 v62, v62
	s_waitcnt lgkmcnt(3)
	v_mfma_f32_32x32x16_bf16 v[18:33], v[188:191], v[42:45], v[18:33]
	ds_read_b128 v[172:175], v217 offset:35936
	v_add_f32_e32 v197, v59, v197
	v_exp_f32_e32 v63, v63
	v_add_f32_e32 v171, v60, v171
	v_exp_f32_e32 v64, v64
	s_waitcnt lgkmcnt(3)
	v_mfma_f32_32x32x16_bf16 v[2:17], v[192:195], v[42:45], v[2:17]
	ds_read_b128 v[176:179], v217 offset:40544
	s_waitcnt vmcnt(3)
	ds_write_b128 v228, v[130:133] offset:13312
	ds_write_b128 v238, v[134:137] offset:13312
	ds_write2_b64 v225, v[142:143], v[144:145] offset1:2
	v_add_f32_e32 v197, v61, v197
	v_exp_f32_e32 v65, v65
	v_add_f32_e32 v171, v62, v171
	v_add_f32_e32 v197, v63, v197
	v_cvt_pk_bf16_f32 v58, v58, v59
	s_waitcnt lgkmcnt(6)
	v_mfma_f32_32x32x16_bf16 v[18:33], v[162:165], v[50:53], v[18:33]
	v_add_f32_e32 v171, v64, v171
	v_cvt_pk_bf16_f32 v59, v60, v61
	v_add_f32_e32 v197, v65, v197
	v_cvt_pk_bf16_f32 v60, v62, v63
	v_cvt_pk_bf16_f32 v61, v64, v65
	v_max3_f32 v1, v66, v67, v68
	s_waitcnt lgkmcnt(5)
	v_mfma_f32_32x32x16_bf16 v[2:17], v[166:169], v[50:53], v[2:17]
	v_max3_f32 v170, v69, v70, v71
	v_max3_f32 v1, v1, v72, v73
	v_max3_f32 v170, v170, v74, v75
	v_max3_f32 v1, v1, v76, v77
	v_max3_f32 v170, v170, v78, v79
	v_max3_f32 v1, v1, v80, v81
	v_max3_f32 v170, v170, v82, v83
	s_waitcnt lgkmcnt(4)
	v_mfma_f32_32x32x16_bf16 v[18:33], v[172:175], v[58:61], v[18:33]
	v_max3_f32 v1, v1, v84, v85
	v_max3_f32 v170, v170, v86, v87
	v_max3_f32 v1, v1, v88, v89
	v_max3_f32 v170, v170, v90, v91
	v_max3_f32 v1, v1, v92, v93
	v_max3_f32 v170, v170, v94, v95
	s_waitcnt lgkmcnt(3)
	v_mfma_f32_32x32x16_bf16 v[2:17], v[176:179], v[58:61], v[2:17]
	v_max3_f32 v1, v1, v96, v97
	v_max_f32_e32 v1, v1, v170
	v_mov_b32_e32 v170, v1
	v_add_f32_e32 v171, v197, v171
	s_nop 0
	v_permlane32_swap_b32_e32 v1, v170
	v_max_f32_e32 v1, v1, v170
	v_cmp_lt_f32_e32 vcc, s93, v1
	s_cbranch_vccnz .Lmf_slow_1
